# in-proj epilogue: 8 row-ssq loads issued together instead of 8 serialized round trips (on top of P6 batching)
# speedup vs baseline: 1.0304x; 1.0027x over previous
;     DI void operator()(const f32x4 (&acc)[2][2][4][2], const Unit& u, int wr, int wc, int fr, int fq) const {
;         int row0 = u.pm * BM + wr * 64 + fr, col0 = u.pn * BM + wc * 32 + 8 * fq;
;         asm volatile("" : "+v"(row0), "+v"(col0));
;         float rstd[2][4];
; #pragma unroll
;         for (int ai = 0; ai < 2; ++ai)
; #pragma unroll
;             for (int m = 0; m < 4; ++m) rstd[ai][m] = rsqrtf(ssq[row0 + ai * HALF + m * 16] * (1.0f / DM) + EPS);
;         if (u.pn < NHT) {
;             const int hs = 4 * u.pn + wc;
.LBB0_133:
	s_lshl_b32 s4, s10, 8
	v_lshl_add_u32 v170, s2, 8, v147
	v_or_b32_e32 v130, s4, v197
	s_mov_b64 s[2:3], -1
	v_ashrrev_i32_e32 v171, 31, v170
	v_lshl_add_u64 v[132:133], v[170:171], 2, s[58:59]
	global_load_dword v172, v[132:133], off
	global_load_dword v168, v[132:133], off offset:64
	global_load_dword v166, v[132:133], off offset:128
	global_load_dword v164, v[132:133], off offset:192
	global_load_dword v162, v[132:133], off offset:512
	global_load_dword v160, v[132:133], off offset:576
	global_load_dword v158, v[132:133], off offset:640
	global_load_dword v128, v[132:133], off offset:704
	v_add_u32_e32 v222, 16, v170
	v_add_u32_e32 v211, 32, v170
	v_add_u32_e32 v209, 48, v170
	v_add_u32_e32 v207, 0x80, v170
	v_add_u32_e32 v205, 0x90, v170
	v_add_u32_e32 v203, 0xa0, v170
	v_add_u32_e32 v201, 0xb0, v170
	v_ashrrev_i32_e32 v223, 31, v222
	v_ashrrev_i32_e32 v221, 31, v211
	v_ashrrev_i32_e32 v210, 31, v209
	v_ashrrev_i32_e32 v208, 31, v207
	v_ashrrev_i32_e32 v206, 31, v205
	v_ashrrev_i32_e32 v204, 31, v203
	v_ashrrev_i32_e32 v202, 31, v201
	s_cmp_lt_i32 s10, 19
	s_waitcnt vmcnt(0)
	v_fmamk_f32 v172, v172, 0x3a000000, v218
	v_cmp_gt_f32_e32 vcc, s33, v172
	v_mul_f32_e32 v131, 0x4b800000, v172
	s_nop 0
	v_cndmask_b32_e32 v172, v172, v131, vcc
	v_rsq_f32_e32 v172, v172
	s_nop 0
	v_mul_f32_e32 v131, 0x45800000, v172
	v_cndmask_b32_e32 v172, v172, v131, vcc
	v_fmamk_f32 v168, v168, 0x3a000000, v218
	v_cmp_gt_f32_e32 vcc, s33, v168
	v_mul_f32_e32 v131, 0x4b800000, v168
	s_nop 0
	v_cndmask_b32_e32 v168, v168, v131, vcc
	v_rsq_f32_e32 v168, v168
	s_nop 0
	v_mul_f32_e32 v131, 0x45800000, v168
	v_cndmask_b32_e32 v168, v168, v131, vcc
	v_fmamk_f32 v166, v166, 0x3a000000, v218
	v_cmp_gt_f32_e32 vcc, s33, v166
	v_mul_f32_e32 v131, 0x4b800000, v166
	s_nop 0
	v_cndmask_b32_e32 v166, v166, v131, vcc
	v_rsq_f32_e32 v166, v166
	s_nop 0
	v_mul_f32_e32 v131, 0x45800000, v166
	v_cndmask_b32_e32 v166, v166, v131, vcc
	v_fmamk_f32 v164, v164, 0x3a000000, v218
	v_cmp_gt_f32_e32 vcc, s33, v164
	v_mul_f32_e32 v131, 0x4b800000, v164
	s_nop 0
	v_cndmask_b32_e32 v164, v164, v131, vcc
	v_rsq_f32_e32 v164, v164
	s_nop 0
	v_mul_f32_e32 v131, 0x45800000, v164
	v_cndmask_b32_e32 v164, v164, v131, vcc
	v_fmamk_f32 v162, v162, 0x3a000000, v218
	v_cmp_gt_f32_e32 vcc, s33, v162
	v_mul_f32_e32 v131, 0x4b800000, v162
	s_nop 0
	v_cndmask_b32_e32 v162, v162, v131, vcc
	v_rsq_f32_e32 v162, v162
	s_nop 0
	v_mul_f32_e32 v131, 0x45800000, v162
	v_cndmask_b32_e32 v162, v162, v131, vcc
	v_fmamk_f32 v160, v160, 0x3a000000, v218
	v_cmp_gt_f32_e32 vcc, s33, v160
	v_mul_f32_e32 v131, 0x4b800000, v160
	s_nop 0
	v_cndmask_b32_e32 v160, v160, v131, vcc
	v_rsq_f32_e32 v160, v160
	s_nop 0
	v_mul_f32_e32 v131, 0x45800000, v160
	v_cndmask_b32_e32 v160, v160, v131, vcc
	v_fmamk_f32 v158, v158, 0x3a000000, v218
	v_cmp_gt_f32_e32 vcc, s33, v158
	v_mul_f32_e32 v131, 0x4b800000, v158
	s_nop 0
	v_cndmask_b32_e32 v158, v158, v131, vcc
	v_rsq_f32_e32 v158, v158
	s_nop 0
	v_mul_f32_e32 v131, 0x45800000, v158
	v_cndmask_b32_e32 v158, v158, v131, vcc
	v_fmamk_f32 v128, v128, 0x3a000000, v218
	v_cmp_gt_f32_e32 vcc, s33, v128
	v_mul_f32_e32 v131, 0x4b800000, v128
	s_nop 0
	v_cndmask_b32_e32 v128, v128, v131, vcc
	v_rsq_f32_e32 v128, v128
	s_nop 0
	v_mul_f32_e32 v131, 0x45800000, v128
	v_cndmask_b32_e32 v156, v128, v131, vcc
	s_cbranch_scc1 .LBB0_199
	s_or_b32 s8, s4, s83
	s_cmpk_lt_i32 s8, 0x1da0
	s_cselect_b64 s[2:3], -1, 0
	s_cmpk_lt_i32 s8, 0x25a0
	s_cselect_b64 s[6:7], -1, 0
	s_cmpk_gt_i32 s8, 0x1d9f
	v_pk_mul_f32 v[134:135], v[124:125], v[172:173] op_sel_hi:[1,0]
	v_pk_mul_f32 v[132:133], v[120:121], v[172:173] op_sel_hi:[1,0]
	v_pk_mul_f32 v[136:137], v[126:127], v[172:173] op_sel_hi:[1,0]
	v_pk_mul_f32 v[174:175], v[122:123], v[172:173] op_sel_hi:[1,0]
	s_mov_b64 s[4:5], -1
	s_cbranch_scc1 .LBB0_136
	s_mov_b64 s[4:5], 0
